# phase 0 converts 1536 tiles; gate-up tail hosts 1280
# baseline (speedup 1.0000x reference)
.LBB0_941:
	s_add_i32 s17, s0, 0xd60
	s_movk_i32 s10, 0x80
	s_movk_i32 s11, 0x12e0
	s_cmp_eq_u32 s30, 16
	s_cbranch_scc0 .Lconv16_skip
	s_add_i32 s17, s0, 0x1760
	s_movk_i32 s11, 0x1aa0

.LBB0_943:
	s_andn2_b64 vcc, exec, s[6:7]
	s_cbranch_vccnz .LBB0_945
	s_add_i32 s17, s0, 0x5e0
	s_movk_i32 s10, 0xe0
	s_movk_i32 s11, 0xde0

.LBB0_946:
	s_and_b64 s[4:5], s[4:5], exec
	s_movk_i32 s1, 0x600
	s_cselect_b32 s11, s1, 0x1aa0
	s_mov_b32 s17, s0
	s_mov_b32 s10, s50
